# M2: u loaded as two dwordx4 + in-register quad transpose, o stored as two dwordx4
# speedup vs baseline: 1.0169x; 1.0031x over previous
.LBB0_175:
	s_or_b64 exec, exec, s[6:7]
	s_lshl_b32 s6, s16, 3
	s_and_b32 s6, s6, 56
	s_ashr_i32 s7, s16, 5
	s_add_i32 s10, s6, s7
	s_ashr_i32 s11, s10, 31
	s_lshl_b64 s[8:9], s[10:11], 19
	s_ashr_i32 s6, s10, 3
	s_and_b32 s17, s7, 7
	s_lshl_b64 s[12:13], s[10:11], 18
	v_lshl_add_u64 v[12:13], v[82:83], 0, s[8:9]
	v_lshl_add_u64 v[20:21], v[84:85], 0, s[8:9]
	s_lshl_b64 s[8:9], s[10:11], 5
	s_lshl_b64 s[10:11], s[10:11], 7
	v_readlane_b32 s7, v250, 22
	s_add_u32 s10, s7, s10
	v_readlane_b32 s7, v250, 23
	s_addc_u32 s11, s7, s11
	s_lshl_b32 s7, s16, 2
	s_and_b32 s14, s7, 0x60
	v_or_b32_e32 v144, s14, v80
	v_lshl_add_u64 v[24:25], v[86:87], 0, s[12:13]
	v_or_b32_e32 v102, v144, v97
	s_waitcnt lgkmcnt(0)
	s_barrier
	global_load_dwordx4 v[0:3], v[12:13], off
	global_load_dwordx4 v[4:7], v[12:13], off offset:64
	global_load_dwordx4 v[8:11], v[12:13], off offset:128
	s_nop 0
	global_load_dwordx4 v[12:15], v[12:13], off offset:192
	s_nop 0
	global_load_dwordx4 v[16:19], v[20:21], off
	global_load_dwordx4 v[28:31], v[24:25], off
	s_nop 0
	global_load_dwordx4 v[20:23], v[20:21], off offset:64
	s_nop 0
	global_load_dwordx4 v[32:35], v[24:25], off offset:64
	v_or_b32_e32 v24, s12, v102
	v_mov_b32_e32 v25, s13
	v_or_b32_e32 v104, v144, v103
	v_lshl_add_u64 v[26:27], v[24:25], 2, s[82:83]
	v_or_b32_e32 v24, s12, v104
	v_or_b32_e32 v106, v144, v105
	global_load_dword v56, v[26:27], off
	v_lshl_add_u64 v[26:27], v[24:25], 2, s[82:83]
	v_or_b32_e32 v24, s12, v106
	v_or_b32_e32 v108, v144, v107
	v_or_b32_e32 v36, 16, v144
	global_load_dword v57, v[26:27], off
	v_lshl_add_u64 v[26:27], v[24:25], 2, s[82:83]
	v_or_b32_e32 v24, s12, v108
	v_or_b32_e32 v110, v36, v97
	global_load_dword v58, v[26:27], off
	v_lshl_add_u64 v[26:27], v[24:25], 2, s[82:83]
	v_or_b32_e32 v24, s12, v110
	v_or_b32_e32 v112, v36, v103
	global_load_dword v59, v[26:27], off
	v_lshl_add_u64 v[26:27], v[24:25], 2, s[82:83]
	v_or_b32_e32 v24, s12, v112
	v_or_b32_e32 v114, v36, v105
	global_load_dword v60, v[26:27], off
	v_lshl_add_u64 v[26:27], v[24:25], 2, s[82:83]
	v_or_b32_e32 v24, s12, v114
	v_or_b32_e32 v116, v36, v107
	global_load_dword v61, v[26:27], off
	v_lshl_add_u64 v[26:27], v[24:25], 2, s[82:83]
	v_or_b32_e32 v24, s12, v116
	v_lshl_add_u64 v[24:25], v[24:25], 2, s[82:83]
	global_load_dword v118, v145, s[10:11]
	global_load_dword v62, v[26:27], off
	global_load_dword v63, v[24:25], off
	s_ashr_i32 s7, s6, 31
	s_lshl_b32 s15, s17, 9
	v_readlane_b32 s12, v250, 20
	s_add_u32 s12, s12, s15
	v_readlane_b32 s13, v250, 21
	s_addc_u32 s13, s13, 0
	s_lshl_b32 s14, s14, 2
	s_add_u32 s12, s12, s14
	s_addc_u32 s13, s13, 0
	v_mov_b32_e32 v101, v145
	v_lshl_add_u64 v[120:121], s[12:13], 0, v[100:101]
	s_lshl_b64 s[12:13], s[6:7], 23
	s_or_b32 s14, s12, s15
	s_lshl_b32 s15, s16, 4
	s_and_b32 s15, s15, 0x180
	s_or_b32 s14, s14, s15
	s_mov_b32 s15, s13
	v_mov_b32_e32 v24, 0
	v_lshl_add_u64 v[122:123], v[98:99], 0, s[14:15]
	v_mov_b32_e32 v125, s13
	v_or_b32_e32 v124, s12, v96
	s_mov_b64 s[12:13], 0
	s_mov_b32 s18, 1
	v_mov_b32_e32 v25, v24
	v_mov_b32_e32 v26, v24
	v_mov_b32_e32 v27, v24
	v_mov_b32_e32 v36, v24
	v_mov_b32_e32 v37, v24
	v_mov_b32_e32 v38, v24
	v_mov_b32_e32 v39, v24
	v_and_b32_e32 v152, 1, v160
	v_sub_u32_e32 v152, 0, v152
	v_bfe_u32 v153, v160, 1, 1
	v_sub_u32_e32 v153, 0, v153
	v_and_b32_e32 v171, 3, v160
	v_mul_u32_u24_e32 v191, 0xffc, v171
	v_mul_u32_u24_e32 v171, 0x7f, v171
	v_add_u32_e32 v171, v171, v102
	s_mov_b32 s56, 1
	s_add_u32 s14, s8, s56
	s_addc_u32 s15, s9, 0
	s_lshl_b64 s[20:21], s[14:15], 13
	s_lshl_b64 s[14:15], s[14:15], 14
	v_lshl_add_u64 v[224:225], v[82:83], 0, s[14:15]
	v_lshl_add_u64 v[236:237], v[84:85], 0, s[14:15]
	s_lshl_b64 s[14:15], s[56:57], 2
	s_add_u32 s14, s10, s14
	v_lshl_add_u64 v[242:243], v[86:87], 0, s[20:21]
	s_addc_u32 s15, s11, s15
	global_load_dwordx4 v[212:215], v[224:225], off
	global_load_dwordx4 v[216:219], v[224:225], off offset:64
	global_load_dwordx4 v[220:223], v[224:225], off offset:128
	s_nop 0
	global_load_dwordx4 v[224:227], v[224:225], off offset:192
	s_nop 0
	global_load_dwordx4 v[228:231], v[236:237], off
	global_load_dwordx4 v[232:235], v[242:243], off
	s_nop 0
	global_load_dwordx4 v[236:239], v[236:237], off offset:64
	s_nop 0
	global_load_dwordx4 v[242:245], v[242:243], off offset:64
	global_load_dword v143, v145, s[14:15]
	v_or_b32_e32 v246, s20, v171
	v_mov_b32_e32 v247, s21
	v_lshl_add_u64 v[246:247], v[246:247], 2, s[82:83]
	global_load_dwordx4 v[180:183], v[246:247], off
	global_load_dwordx4 v[184:187], v[246:247], off offset:64
	s_waitcnt vmcnt(11)
	s_branch .Lm2_topA
.Lm2_tailB_r0:
	v_pk_mul_f32 v[26:27], v[26:27], v[118:119] op_sel_hi:[1,0]
	v_pk_mul_f32 v[24:25], v[24:25], v[118:119] op_sel_hi:[1,0]
	v_pk_mul_f32 v[30:31], v[38:39], v[118:119] op_sel_hi:[1,0]
	v_pk_mul_f32 v[28:29], v[36:37], v[118:119] op_sel_hi:[1,0]
	s_waitcnt lgkmcnt(3)
	v_mfma_f32_16x16x32_bf16 v[24:27], v[16:19], v[68:71], v[24:27]
	s_add_u32 s12, s12, 0x40000
	s_addc_u32 s13, s13, 0
	s_add_i32 s18, s18, 1
	s_waitcnt lgkmcnt(1)
	v_mfma_f32_16x16x32_bf16 v[16:19], v[16:19], v[64:67], v[28:31]
	s_nop 0
	s_waitcnt vmcnt(9)
	v_mov_b64_e32 v[32:33], v[52:53]
	s_cmp_eq_u32 s12, 0x800000
	v_mov_b64_e32 v[34:35], v[54:55]
	v_mfma_f32_16x16x32_bf16 v[24:27], v[20:23], v[56:59], v[24:27]
	v_mov_b64_e32 v[28:29], v[44:45]
	s_nop 0
	s_nop 0
	s_nop 0
	s_nop 0
	s_waitcnt lgkmcnt(0)
	v_mfma_f32_16x16x32_bf16 v[36:39], v[20:23], v[60:63], v[16:19]
	v_cvt_pk_bf16_f32 v16, v24, v25
	v_cvt_pk_bf16_f32 v17, v26, v27
	ds_write_b64 v119, v[16:17]
	v_cvt_pk_bf16_f32 v16, v36, v37
	v_cvt_pk_bf16_f32 v17, v38, v39
	ds_write_b64 v119, v[16:17] offset:4352
	s_waitcnt lgkmcnt(0)
	s_barrier
	s_waitcnt vmcnt(9)
	v_mov_b64_e32 v[16:17], v[40:41]
	v_mov_b64_e32 v[20:21], v[48:49]
	s_nop 0
	s_nop 0
	s_nop 0
	s_nop 0
	s_nop 0
	s_nop 0
	s_nop 0
	s_nop 0
	s_nop 0
	s_nop 0
	s_nop 0
	s_nop 0
	v_mov_b64_e32 v[30:31], v[46:47]
	v_mov_b64_e32 v[18:19], v[42:43]
	v_mov_b64_e32 v[22:23], v[50:51]
	v_mov_b32_e32 v118, v101
	v_bfi_b32 v192, v153, v126, v128
	v_bfi_b32 v193, v153, v127, v129
	s_nop 1
	v_mov_b32_dpp v194, v192 quad_perm:[2,3,0,1] row_mask:0xf bank_mask:0xf
	v_mov_b32_dpp v195, v193 quad_perm:[2,3,0,1] row_mask:0xf bank_mask:0xf
	s_nop 0
	v_bfi_b32 v126, v153, v194, v126
	v_bfi_b32 v127, v153, v195, v127
	v_bfi_b32 v128, v153, v128, v194
	v_bfi_b32 v129, v153, v129, v195
	v_bfi_b32 v192, v152, v126, v127
	v_bfi_b32 v193, v152, v128, v129
	s_nop 1
	v_mov_b32_dpp v194, v192 quad_perm:[1,0,3,2] row_mask:0xf bank_mask:0xf
	v_mov_b32_dpp v195, v193 quad_perm:[1,0,3,2] row_mask:0xf bank_mask:0xf
	s_nop 0
	v_bfi_b32 v56, v152, v194, v126
	v_bfi_b32 v57, v152, v127, v194
	v_bfi_b32 v58, v152, v195, v128
	v_bfi_b32 v59, v152, v129, v195
	v_bfi_b32 v192, v153, v130, v132
	v_bfi_b32 v193, v153, v131, v133
	s_nop 1
	v_mov_b32_dpp v194, v192 quad_perm:[2,3,0,1] row_mask:0xf bank_mask:0xf
	v_mov_b32_dpp v195, v193 quad_perm:[2,3,0,1] row_mask:0xf bank_mask:0xf
	s_nop 0
	v_bfi_b32 v130, v153, v194, v130
	v_bfi_b32 v131, v153, v195, v131
	v_bfi_b32 v132, v153, v132, v194
	v_bfi_b32 v133, v153, v133, v195
	v_bfi_b32 v192, v152, v130, v131
	v_bfi_b32 v193, v152, v132, v133
	s_nop 1
	v_mov_b32_dpp v194, v192 quad_perm:[1,0,3,2] row_mask:0xf bank_mask:0xf
	v_mov_b32_dpp v195, v193 quad_perm:[1,0,3,2] row_mask:0xf bank_mask:0xf
	s_nop 0
	v_bfi_b32 v60, v152, v194, v130
	v_bfi_b32 v61, v152, v131, v194
	v_bfi_b32 v62, v152, v195, v132
	v_bfi_b32 v63, v152, v133, v195
	s_cbranch_scc1 .LBB0_171

.Lm2_skga:
	s_cmp_eq_u64 s[2:3], 0
	s_cbranch_scc1 .Lm2_skua
	v_or_b32_e32 v246, s20, v171
	v_mov_b32_e32 v247, s21
	v_lshl_add_u64 v[246:247], v[246:247], 2, s[82:83]
	global_load_dwordx4 v[126:129], v[246:247], off
	global_load_dwordx4 v[130:133], v[246:247], off offset:64

.Lm2_181a:
	s_andn2_b64 vcc, exec, s[14:15]
	s_cbranch_vccnz .Lm2_tailA_r0
	s_waitcnt lgkmcnt(3)
	v_mfma_f32_16x16x32_bf16 v[72:75], v[28:31], v[68:71], v[72:75]
	s_waitcnt lgkmcnt(1)
	v_mfma_f32_16x16x32_bf16 v[28:31], v[28:31], v[64:67], v[76:79]
	v_mfma_f32_16x16x32_bf16 v[72:75], v[32:35], v[56:59], v[72:75]
	s_waitcnt lgkmcnt(0)
	v_mfma_f32_16x16x32_bf16 v[28:31], v[32:35], v[60:63], v[28:31]
	v_lshl_add_u64 v[32:33], v[124:125], 0, s[12:13]
	v_lshl_add_u64 v[34:35], v[122:123], 0, s[12:13]
	v_add_co_u32_e32 v34, vcc, 0x29d41000, v34
	v_or_b32_e32 v76, 0x1000, v32
	v_mov_b32_e32 v77, v33
	v_addc_co_u32_e32 v35, vcc, 0, v35, vcc
	v_lshl_add_u64 v[76:77], v[120:121], 0, v[76:77]
	v_add_co_u32_e32 v34, vcc, v191, v34
	s_nop 1
	v_addc_co_u32_e32 v35, vcc, 0, v35, vcc
	v_bfi_b32 v192, v153, v72, v74
	v_bfi_b32 v193, v153, v73, v75
	s_nop 1
	v_mov_b32_dpp v194, v192 quad_perm:[2,3,0,1] row_mask:0xf bank_mask:0xf
	v_mov_b32_dpp v195, v193 quad_perm:[2,3,0,1] row_mask:0xf bank_mask:0xf
	s_nop 0
	v_bfi_b32 v72, v153, v194, v72
	v_bfi_b32 v73, v153, v195, v73
	v_bfi_b32 v74, v153, v74, v194
	v_bfi_b32 v75, v153, v75, v195
	v_bfi_b32 v192, v152, v72, v73
	v_bfi_b32 v193, v152, v74, v75
	s_nop 1
	v_mov_b32_dpp v194, v192 quad_perm:[1,0,3,2] row_mask:0xf bank_mask:0xf
	v_mov_b32_dpp v195, v193 quad_perm:[1,0,3,2] row_mask:0xf bank_mask:0xf
	s_nop 0
	v_bfi_b32 v72, v152, v194, v72
	v_bfi_b32 v73, v152, v73, v194
	v_bfi_b32 v74, v152, v195, v74
	v_bfi_b32 v75, v152, v75, v195
	v_bfi_b32 v192, v153, v28, v30
	v_bfi_b32 v193, v153, v29, v31
	s_nop 1
	v_mov_b32_dpp v194, v192 quad_perm:[2,3,0,1] row_mask:0xf bank_mask:0xf
	v_mov_b32_dpp v195, v193 quad_perm:[2,3,0,1] row_mask:0xf bank_mask:0xf
	s_nop 0
	v_bfi_b32 v28, v153, v194, v28
	v_bfi_b32 v29, v153, v195, v29
	v_bfi_b32 v30, v153, v30, v194
	v_bfi_b32 v31, v153, v31, v195
	v_bfi_b32 v192, v152, v28, v29
	v_bfi_b32 v193, v152, v30, v31
	s_nop 1
	v_mov_b32_dpp v194, v192 quad_perm:[1,0,3,2] row_mask:0xf bank_mask:0xf
	v_mov_b32_dpp v195, v193 quad_perm:[1,0,3,2] row_mask:0xf bank_mask:0xf
	s_nop 0
	v_bfi_b32 v28, v152, v194, v28
	v_bfi_b32 v29, v152, v29, v194
	v_bfi_b32 v30, v152, v195, v30
	v_bfi_b32 v31, v152, v31, v195
	global_store_dwordx4 v[34:35], v[72:75], off
	global_store_dwordx4 v[34:35], v[28:31], off offset:64
	s_branch .Lm2_tailA_r1
.Lm2_tailA_r0:
	v_pk_mul_f32 v[26:27], v[26:27], v[118:119] op_sel_hi:[1,0]
	v_pk_mul_f32 v[24:25], v[24:25], v[118:119] op_sel_hi:[1,0]
	v_pk_mul_f32 v[30:31], v[38:39], v[118:119] op_sel_hi:[1,0]
	v_pk_mul_f32 v[28:29], v[36:37], v[118:119] op_sel_hi:[1,0]
	s_waitcnt lgkmcnt(3)
	v_mfma_f32_16x16x32_bf16 v[24:27], v[16:19], v[68:71], v[24:27]
	s_add_u32 s12, s12, 0x40000
	s_addc_u32 s13, s13, 0
	s_add_i32 s18, s18, 1
	s_waitcnt lgkmcnt(1)
	v_mfma_f32_16x16x32_bf16 v[16:19], v[16:19], v[64:67], v[28:31]
	s_nop 0
	s_waitcnt vmcnt(9)
	v_mov_b64_e32 v[32:33], v[242:243]
	s_cmp_eq_u32 s12, 0x800000
	v_mov_b64_e32 v[34:35], v[244:245]
	v_mfma_f32_16x16x32_bf16 v[24:27], v[20:23], v[56:59], v[24:27]
	v_mov_b64_e32 v[28:29], v[232:233]
	s_nop 0
	s_nop 0
	s_nop 0
	s_nop 0
	s_waitcnt lgkmcnt(0)
	v_mfma_f32_16x16x32_bf16 v[36:39], v[20:23], v[60:63], v[16:19]
	v_cvt_pk_bf16_f32 v16, v24, v25
	v_cvt_pk_bf16_f32 v17, v26, v27
	ds_write_b64 v119, v[16:17]
	v_cvt_pk_bf16_f32 v16, v36, v37
	v_cvt_pk_bf16_f32 v17, v38, v39
	ds_write_b64 v119, v[16:17] offset:4352
	s_waitcnt lgkmcnt(0)
	s_barrier
	s_waitcnt vmcnt(9)
	v_mov_b64_e32 v[16:17], v[228:229]
	v_mov_b64_e32 v[20:21], v[236:237]
	s_nop 0
	s_nop 0
	s_nop 0
	s_nop 0
	s_nop 0
	s_nop 0
	s_nop 0
	s_nop 0
	s_nop 0
	s_nop 0
	s_nop 0
	s_nop 0
	v_mov_b64_e32 v[30:31], v[234:235]
	v_mov_b64_e32 v[18:19], v[230:231]
	v_mov_b64_e32 v[22:23], v[238:239]
	v_mov_b32_e32 v118, v143
	v_bfi_b32 v192, v153, v180, v182
	v_bfi_b32 v193, v153, v181, v183
	s_nop 1
	v_mov_b32_dpp v194, v192 quad_perm:[2,3,0,1] row_mask:0xf bank_mask:0xf
	v_mov_b32_dpp v195, v193 quad_perm:[2,3,0,1] row_mask:0xf bank_mask:0xf
	s_nop 0
	v_bfi_b32 v180, v153, v194, v180
	v_bfi_b32 v181, v153, v195, v181
	v_bfi_b32 v182, v153, v182, v194
	v_bfi_b32 v183, v153, v183, v195
	v_bfi_b32 v192, v152, v180, v181
	v_bfi_b32 v193, v152, v182, v183
	s_nop 1
	v_mov_b32_dpp v194, v192 quad_perm:[1,0,3,2] row_mask:0xf bank_mask:0xf
	v_mov_b32_dpp v195, v193 quad_perm:[1,0,3,2] row_mask:0xf bank_mask:0xf
	s_nop 0
	v_bfi_b32 v56, v152, v194, v180
	v_bfi_b32 v57, v152, v181, v194
	v_bfi_b32 v58, v152, v195, v182
	v_bfi_b32 v59, v152, v183, v195
	v_bfi_b32 v192, v153, v184, v186
	v_bfi_b32 v193, v153, v185, v187
	s_nop 1
	v_mov_b32_dpp v194, v192 quad_perm:[2,3,0,1] row_mask:0xf bank_mask:0xf
	v_mov_b32_dpp v195, v193 quad_perm:[2,3,0,1] row_mask:0xf bank_mask:0xf
	s_nop 0
	v_bfi_b32 v184, v153, v194, v184
	v_bfi_b32 v185, v153, v195, v185
	v_bfi_b32 v186, v153, v186, v194
	v_bfi_b32 v187, v153, v187, v195
	v_bfi_b32 v192, v152, v184, v185
	v_bfi_b32 v193, v152, v186, v187
	s_nop 1
	v_mov_b32_dpp v194, v192 quad_perm:[1,0,3,2] row_mask:0xf bank_mask:0xf
	v_mov_b32_dpp v195, v193 quad_perm:[1,0,3,2] row_mask:0xf bank_mask:0xf
	s_nop 0
	v_bfi_b32 v60, v152, v194, v184
	v_bfi_b32 v61, v152, v185, v194
	v_bfi_b32 v62, v152, v195, v186
	v_bfi_b32 v63, v152, v187, v195
	s_cbranch_scc1 .LBB0_171

.Lm2_skgb:
	s_cmp_eq_u64 s[2:3], 0
	s_cbranch_scc1 .Lm2_skub
	v_or_b32_e32 v246, s20, v171
	v_mov_b32_e32 v247, s21
	v_lshl_add_u64 v[246:247], v[246:247], 2, s[82:83]
	global_load_dwordx4 v[180:183], v[246:247], off
	global_load_dwordx4 v[184:187], v[246:247], off offset:64

.Lm2_tailA_r1:
	v_pk_mul_f32 v[26:27], v[26:27], v[118:119] op_sel_hi:[1,0]
	v_pk_mul_f32 v[24:25], v[24:25], v[118:119] op_sel_hi:[1,0]
	v_pk_mul_f32 v[30:31], v[38:39], v[118:119] op_sel_hi:[1,0]
	v_pk_mul_f32 v[28:29], v[36:37], v[118:119] op_sel_hi:[1,0]
	s_waitcnt lgkmcnt(3)
	v_mfma_f32_16x16x32_bf16 v[24:27], v[16:19], v[68:71], v[24:27]
	s_add_u32 s12, s12, 0x40000
	s_addc_u32 s13, s13, 0
	s_add_i32 s18, s18, 1
	s_waitcnt lgkmcnt(1)
	v_mfma_f32_16x16x32_bf16 v[16:19], v[16:19], v[64:67], v[28:31]
	s_nop 0
	s_waitcnt vmcnt(11)
	v_mov_b64_e32 v[32:33], v[242:243]
	s_cmp_eq_u32 s12, 0x800000
	v_mov_b64_e32 v[34:35], v[244:245]
	v_mfma_f32_16x16x32_bf16 v[24:27], v[20:23], v[56:59], v[24:27]
	v_mov_b64_e32 v[28:29], v[232:233]
	s_nop 0
	s_nop 0
	s_nop 0
	s_nop 0
	s_waitcnt lgkmcnt(0)
	v_mfma_f32_16x16x32_bf16 v[36:39], v[20:23], v[60:63], v[16:19]
	v_cvt_pk_bf16_f32 v16, v24, v25
	v_cvt_pk_bf16_f32 v17, v26, v27
	ds_write_b64 v119, v[16:17]
	v_cvt_pk_bf16_f32 v16, v36, v37
	v_cvt_pk_bf16_f32 v17, v38, v39
	ds_write_b64 v119, v[16:17] offset:4352
	s_waitcnt lgkmcnt(0)
	s_barrier
	s_waitcnt vmcnt(11)
	v_mov_b64_e32 v[16:17], v[228:229]
	v_mov_b64_e32 v[20:21], v[236:237]
	s_nop 0
	s_nop 0
	s_nop 0
	s_nop 0
	s_nop 0
	s_nop 0
	s_nop 0
	s_nop 0
	s_nop 0
	s_nop 0
	s_nop 0
	s_nop 0
	v_mov_b64_e32 v[30:31], v[234:235]
	v_mov_b64_e32 v[18:19], v[230:231]
	v_mov_b64_e32 v[22:23], v[238:239]
	v_mov_b32_e32 v118, v143
	s_cbranch_scc1 .LBB0_171
	s_branch .Lm2_topB
.Lm2_tailB_r1:
	v_pk_mul_f32 v[26:27], v[26:27], v[118:119] op_sel_hi:[1,0]
	v_pk_mul_f32 v[24:25], v[24:25], v[118:119] op_sel_hi:[1,0]
	v_pk_mul_f32 v[30:31], v[38:39], v[118:119] op_sel_hi:[1,0]
	v_pk_mul_f32 v[28:29], v[36:37], v[118:119] op_sel_hi:[1,0]
	s_waitcnt lgkmcnt(3)
	v_mfma_f32_16x16x32_bf16 v[24:27], v[16:19], v[68:71], v[24:27]
	s_add_u32 s12, s12, 0x40000
	s_addc_u32 s13, s13, 0
	s_add_i32 s18, s18, 1
	s_waitcnt lgkmcnt(1)
	v_mfma_f32_16x16x32_bf16 v[16:19], v[16:19], v[64:67], v[28:31]
	s_nop 0
	s_waitcnt vmcnt(11)
	v_mov_b64_e32 v[32:33], v[52:53]
	s_cmp_eq_u32 s12, 0x800000
	v_mov_b64_e32 v[34:35], v[54:55]
	v_mfma_f32_16x16x32_bf16 v[24:27], v[20:23], v[56:59], v[24:27]
	v_mov_b64_e32 v[28:29], v[44:45]
	s_nop 0
	s_nop 0
	s_nop 0
	s_nop 0
	s_waitcnt lgkmcnt(0)
	v_mfma_f32_16x16x32_bf16 v[36:39], v[20:23], v[60:63], v[16:19]
	v_cvt_pk_bf16_f32 v16, v24, v25
	v_cvt_pk_bf16_f32 v17, v26, v27
	ds_write_b64 v119, v[16:17]
	v_cvt_pk_bf16_f32 v16, v36, v37
	v_cvt_pk_bf16_f32 v17, v38, v39
	ds_write_b64 v119, v[16:17] offset:4352
	s_waitcnt lgkmcnt(0)
	s_barrier
	s_waitcnt vmcnt(11)
	v_mov_b64_e32 v[16:17], v[40:41]
	v_mov_b64_e32 v[20:21], v[48:49]
	s_nop 0
	s_nop 0
	s_nop 0
	s_nop 0
	s_nop 0
	s_nop 0
	s_nop 0
	s_nop 0
	s_nop 0
	s_nop 0
	s_nop 0
	s_nop 0
	v_mov_b64_e32 v[30:31], v[46:47]
	v_mov_b64_e32 v[18:19], v[42:43]
	v_mov_b64_e32 v[22:23], v[50:51]
	v_mov_b32_e32 v118, v101
	s_cbranch_scc1 .LBB0_171
	s_branch .Lm2_topA
